# band-loop max trims; fused epilogue pass 1 (bf16 residual): residual loads issued three rows ahead
# speedup vs baseline: 1.0351x; 1.0022x over previous
.LBB0_381:
	v_add_u32_e32 v35, s48, v249
	ds_read_b64_tr_b16 v[194:195], v35 offset:24576
	ds_read_b64_tr_b16 v[196:197], v35 offset:25088
	v_add_f32_e32 v36, v82, v83
	v_add_f32_e32 v36, v84, v36
	v_add_f32_e32 v36, v85, v36
	v_add_f32_e32 v36, v86, v36
	v_add_f32_e32 v36, v87, v36
	v_cvt_pk_bf16_f32 v158, v82, v83
	v_cvt_pk_bf16_f32 v159, v84, v85
	s_waitcnt lgkmcnt(9)
	v_mfma_f32_32x32x16_bf16 v[114:129], v[190:193], v[150:153], v[66:81]
	ds_read_b64_tr_b16 v[190:191], v35 offset:28672
	ds_read_b64_tr_b16 v[192:193], v35 offset:29184
	s_waitcnt lgkmcnt(10)
	v_mfma_f32_32x32x16_bf16 v[66:81], v[186:189], v[150:153], v[66:81]
	v_add_f32_e32 v36, v88, v36
	v_add_f32_e32 v36, v89, v36
	v_add_f32_e32 v36, v90, v36
	v_add_f32_e32 v36, v91, v36
	v_cvt_pk_bf16_f32 v160, v86, v87
	v_cvt_pk_bf16_f32 v161, v88, v89
	ds_read_b64_tr_b16 v[84:85], v35 offset:25600
	ds_read_b64_tr_b16 v[86:87], v35 offset:26112
	v_add_f32_e32 v36, v92, v36
	v_add_f32_e32 v36, v93, v36
	v_add_f32_e32 v36, v94, v36
	v_add_f32_e32 v36, v95, v36
	v_cvt_pk_bf16_f32 v154, v90, v91
	v_cvt_pk_bf16_f32 v155, v92, v93
	s_waitcnt lgkmcnt(11)
	v_mfma_f32_32x32x16_bf16 v[114:129], v[182:185], v[142:145], v[114:129]
	ds_read_b64_tr_b16 v[88:89], v35 offset:29696
	ds_read_b64_tr_b16 v[90:91], v35 offset:30208
	s_waitcnt lgkmcnt(12)
	v_mfma_f32_32x32x16_bf16 v[66:81], v[178:181], v[142:145], v[66:81]
	v_add_f32_e32 v36, v96, v36
	v_add_f32_e32 v36, v97, v36
	v_add_f32_e32 v36, v98, v36
	v_add_f32_e32 v36, v99, v36
	v_cvt_pk_bf16_f32 v156, v94, v95
	v_cvt_pk_bf16_f32 v157, v96, v97
	ds_read_b64_tr_b16 v[92:93], v35 offset:26624
	ds_read_b64_tr_b16 v[94:95], v35 offset:27136
	v_add_f32_e32 v36, v100, v36
	v_add_f32_e32 v36, v101, v36
	v_add_f32_e32 v36, v102, v36
	v_add_f32_e32 v36, v103, v36
	v_cvt_pk_bf16_f32 v146, v98, v99
	v_cvt_pk_bf16_f32 v147, v100, v101
	s_waitcnt lgkmcnt(13)
	v_mfma_f32_32x32x16_bf16 v[114:129], v[174:177], v[134:137], v[114:129]
	ds_read_b64_tr_b16 v[96:97], v35 offset:30720
	ds_read_b64_tr_b16 v[98:99], v35 offset:31232
	s_waitcnt lgkmcnt(14)
	v_mfma_f32_32x32x16_bf16 v[66:81], v[170:173], v[134:137], v[66:81]
	v_add_f32_e32 v36, v104, v36
	v_add_f32_e32 v36, v105, v36
	v_add_f32_e32 v36, v106, v36
	v_add_f32_e32 v36, v107, v36
	v_cvt_pk_bf16_f32 v148, v102, v103
	v_cvt_pk_bf16_f32 v149, v104, v105
	ds_read_b64_tr_b16 v[100:101], v35 offset:27648
	ds_read_b64_tr_b16 v[102:103], v35 offset:28160
	v_add_f32_e32 v36, v108, v36
	v_add_f32_e32 v36, v109, v36
	v_add_f32_e32 v36, v110, v36
	v_add_f32_e32 v36, v111, v36
	v_cvt_pk_bf16_f32 v138, v106, v107
	v_cvt_pk_bf16_f32 v139, v108, v109
	s_waitcnt lgkmcnt(14)
	v_mfma_f32_32x32x16_bf16 v[114:129], v[166:169], v[130:133], v[114:129]
	ds_read_b64_tr_b16 v[104:105], v35 offset:31744
	ds_read_b64_tr_b16 v[106:107], v35 offset:32256
	v_mfma_f32_32x32x16_bf16 v[66:81], v[162:165], v[130:133], v[66:81]
	v_add_f32_e32 v35, v112, v36
	v_add_f32_e32 v35, v113, v35
	v_add_f32_e32 v35, 0, v35
	v_cvt_pk_bf16_f32 v140, v110, v111
	v_cvt_pk_bf16_f32 v141, v112, v113
	v_or_b32_e32 v53, 0xe0, v245
	s_nop 5
	v_pk_add_f32 v[36:37], v[220:221], v[66:67]
	v_or_b32_e32 v52, 0xc0, v245
	v_cmp_le_i32_e32 vcc, v53, v246
	v_or_b32_e32 v54, 0xe1, v245
	v_mov_b32_e32 v215, v214
	v_cndmask_b32_e32 v36, v235, v36, vcc
	v_cmp_lt_i32_e32 vcc, v52, v246
	v_or_b32_e32 v55, 0xe2, v245
	v_pk_add_f32 v[38:39], v[214:215], v[68:69]
	v_cndmask_b32_e32 v53, v235, v115, vcc
	v_cmp_le_i32_e32 vcc, v52, v246
	v_or_b32_e32 v56, 0xe3, v245
	v_or_b32_e32 v57, 0xe8, v245
	v_cndmask_b32_e32 v52, v235, v114, vcc
	v_cmp_le_i32_e32 vcc, v54, v246
	v_or_b32_e32 v54, 0xc2, v245
	v_pk_add_f32 v[40:41], v[214:215], v[70:71]
	v_cndmask_b32_e32 v37, v235, v37, vcc
	v_cmp_le_i32_e32 vcc, v54, v246
	v_or_b32_e32 v58, 0xe9, v245
	v_or_b32_e32 v59, 0xea, v245
	v_cndmask_b32_e32 v54, v235, v116, vcc
	v_cmp_le_i32_e32 vcc, v55, v246
	v_or_b32_e32 v55, 0xc3, v245
	v_pk_add_f32 v[42:43], v[214:215], v[72:73]
	v_cndmask_b32_e32 v38, v235, v38, vcc
	v_cmp_le_i32_e32 vcc, v55, v246
	v_or_b32_e32 v60, 0xeb, v245
	v_or_b32_e32 v61, 0xf0, v245
	v_cndmask_b32_e32 v55, v235, v117, vcc
	v_cmp_le_i32_e32 vcc, v56, v246
	v_or_b32_e32 v56, 0xc8, v245
	v_pk_add_f32 v[44:45], v[214:215], v[74:75]
	v_cndmask_b32_e32 v39, v235, v39, vcc
	v_cmp_le_i32_e32 vcc, v56, v246
	v_or_b32_e32 v62, 0xf1, v245
	v_or_b32_e32 v63, 0xf2, v245
	v_cndmask_b32_e32 v56, v235, v118, vcc
	v_cmp_le_i32_e32 vcc, v57, v246
	v_or_b32_e32 v57, 0xc9, v245
	v_pk_add_f32 v[46:47], v[214:215], v[76:77]
	v_cndmask_b32_e32 v40, v235, v40, vcc
	v_cmp_le_i32_e32 vcc, v57, v246
	v_or_b32_e32 v64, 0xf3, v245
	v_or_b32_e32 v65, 0xf8, v245
	v_cndmask_b32_e32 v57, v235, v119, vcc
	v_cmp_le_i32_e32 vcc, v58, v246
	v_or_b32_e32 v58, 0xca, v245
	v_pk_add_f32 v[48:49], v[214:215], v[78:79]
	v_cndmask_b32_e32 v41, v235, v41, vcc
	v_cmp_le_i32_e32 vcc, v58, v246
	v_or_b32_e32 v66, 0xf9, v245
	v_or_b32_e32 v67, 0xfa, v245
	v_cndmask_b32_e32 v58, v235, v120, vcc
	v_cmp_le_i32_e32 vcc, v59, v246
	v_or_b32_e32 v59, 0xcb, v245
	v_pk_add_f32 v[50:51], v[214:215], v[80:81]
	v_cndmask_b32_e32 v42, v235, v42, vcc
	v_cmp_le_i32_e32 vcc, v59, v246
	v_or_b32_e32 v68, 0xfb, v245
	v_max_f32_e32 v69, v52, v52
	v_cndmask_b32_e32 v59, v235, v121, vcc
	v_cmp_le_i32_e32 vcc, v60, v246
	v_or_b32_e32 v60, 0xd0, v245
	v_add_f32_e32 v34, v34, v35
	v_cndmask_b32_e32 v43, v235, v43, vcc
	v_cmp_le_i32_e32 vcc, v60, v246
	s_nop 1
	v_cndmask_b32_e32 v60, v235, v122, vcc
	v_cmp_le_i32_e32 vcc, v61, v246
	v_or_b32_e32 v61, 0xd1, v245
	s_nop 0
	v_cndmask_b32_e32 v44, v235, v44, vcc
	v_cmp_le_i32_e32 vcc, v61, v246
	s_nop 1
	v_cndmask_b32_e32 v61, v235, v123, vcc
	v_cmp_le_i32_e32 vcc, v62, v246
	v_or_b32_e32 v62, 0xd2, v245
	s_nop 0
	v_cndmask_b32_e32 v45, v235, v45, vcc
	v_cmp_le_i32_e32 vcc, v62, v246
	s_nop 1
	v_cndmask_b32_e32 v62, v235, v124, vcc
	v_cmp_le_i32_e32 vcc, v63, v246
	v_or_b32_e32 v63, 0xd3, v245
	s_nop 0
	v_cndmask_b32_e32 v46, v235, v46, vcc
	v_cmp_le_i32_e32 vcc, v63, v246
	s_nop 1
	v_cndmask_b32_e32 v63, v235, v125, vcc
	v_cmp_le_i32_e32 vcc, v64, v246
	v_or_b32_e32 v64, 0xd8, v245
	s_nop 0
	v_cndmask_b32_e32 v47, v235, v47, vcc
	v_cmp_le_i32_e32 vcc, v64, v246
	s_nop 1
	v_cndmask_b32_e32 v64, v235, v126, vcc
	v_cmp_le_i32_e32 vcc, v65, v246
	v_or_b32_e32 v65, 0xd9, v245
	s_nop 0
	v_cndmask_b32_e32 v48, v235, v48, vcc
	v_cmp_le_i32_e32 vcc, v65, v246
	s_nop 1
	v_cndmask_b32_e32 v65, v235, v127, vcc
	v_cmp_le_i32_e32 vcc, v66, v246
	v_or_b32_e32 v66, 0xda, v245
	s_nop 0
	v_cndmask_b32_e32 v49, v235, v49, vcc
	v_cmp_le_i32_e32 vcc, v66, v246
	s_nop 1
	v_cndmask_b32_e32 v66, v235, v128, vcc
	v_cmp_le_i32_e32 vcc, v67, v246
	v_or_b32_e32 v67, 0xdb, v245
	s_nop 0
	v_cndmask_b32_e32 v50, v235, v50, vcc
	v_cmp_le_i32_e32 vcc, v67, v246
	s_nop 1
	v_cndmask_b32_e32 v67, v235, v129, vcc
	v_cmp_le_i32_e32 vcc, v68, v246
	v_max_f32_e32 v68, v69, v53
	v_max3_f32 v69, v54, v55, v37
	v_max3_f32 v68, v68, v36, v38
	v_max3_f32 v68, v68, v39, v56
	v_max3_f32 v69, v69, v58, v59
	v_max3_f32 v68, v68, v57, v40
	v_max3_f32 v69, v69, v42, v43
	v_max3_f32 v68, v68, v41, v60
	v_max3_f32 v69, v69, v62, v63
	v_max3_f32 v68, v68, v61, v44
	v_max3_f32 v69, v69, v46, v47
	v_cndmask_b32_e32 v51, v235, v51, vcc
	v_max3_f32 v68, v68, v45, v64
	v_max3_f32 v69, v69, v66, v67
	v_max3_f32 v68, v68, v65, v48
	v_max3_f32 v69, v69, v50, v51
	v_max3_f32 v35, v68, v49, v69
	v_mov_b32_e32 v68, v35
	s_nop 1
	v_permlane32_swap_b32_e32 v35, v68
	v_max_f32_e32 v35, v35, v68
	v_cmp_lt_f32_e32 vcc, s88, v35
	s_cmp_lg_u64 vcc, 0
	s_cselect_b64 s[0:1], -1, 0
	s_cbranch_vccnz .LBB0_438

.LBB0_394:
	v_add_f32_e32 v211, v34, v35
	v_max_f32_e32 v34, v36, v37
	v_max3_f32 v35, v38, v39, v99
	v_max3_f32 v34, v34, v98, v100
	v_max3_f32 v34, v34, v101, v40
	v_max3_f32 v35, v35, v42, v43
	v_max3_f32 v34, v34, v41, v102
	v_max3_f32 v35, v35, v104, v105
	v_max3_f32 v34, v34, v103, v44
	v_max3_f32 v35, v35, v46, v47
	v_max3_f32 v34, v34, v45, v106
	v_max3_f32 v35, v35, v108, v109
	v_max3_f32 v34, v34, v107, v48
	v_max3_f32 v35, v35, v50, v51
	v_max3_f32 v34, v34, v49, v110
	v_max3_f32 v35, v35, v112, v113
	v_max3_f32 v34, v34, v111, v35
	v_mov_b32_e32 v35, v34
	s_nop 1
	v_permlane32_swap_b32_e32 v34, v35
	v_max_f32_e32 v34, v34, v35
	v_cmp_lt_f32_e32 vcc, s88, v34
	s_cmp_lg_u64 vcc, 0
	s_cselect_b64 s[54:55], -1, 0
	s_cbranch_vccnz .LBB0_432

.LBB0_409:
	v_max_f32_e32 v51, v82, v83
	v_max3_f32 v114, v84, v85, v99
	v_max3_f32 v51, v51, v98, v100
	v_max3_f32 v51, v51, v101, v86
	v_max3_f32 v114, v114, v88, v89
	v_max3_f32 v51, v51, v87, v102
	v_max3_f32 v114, v114, v104, v105
	v_max3_f32 v51, v51, v103, v90
	v_max3_f32 v114, v114, v92, v93
	v_max3_f32 v51, v51, v91, v106
	v_max3_f32 v114, v114, v108, v109
	v_max3_f32 v51, v51, v107, v94
	v_max3_f32 v114, v114, v96, v97
	v_max3_f32 v51, v51, v95, v110
	v_max3_f32 v114, v114, v112, v113
	v_max3_f32 v51, v51, v111, v114
	v_mov_b32_e32 v114, v51
	s_nop 1
	v_permlane32_swap_b32_e32 v51, v114
	v_max_f32_e32 v51, v51, v114
	v_cmp_lt_f32_e32 vcc, s88, v51
	s_cmp_lg_u64 vcc, 0
	v_fmac_f32_e32 v50, v210, v211
	s_cselect_b64 s[66:67], -1, 0
	s_cbranch_vccnz .LBB0_435

.LBB0_896:
	s_or_b64 exec, exec, s[20:21]
	s_lshl_b32 s0, s30, 5
	s_lshl_b32 s1, s16, 8
	s_or_b32 s0, s1, s0
	v_lshrrev_b32_e32 v130, 2, v148
	v_and_or_b32 v162, v130, 12, s0
	v_add_u32_e32 v150, s17, v152
	s_lshl_b32 s0, s26, 5
	v_ashrrev_i32_e32 v151, 31, v150
	s_and_b32 s0, s0, 0xfffffc00
	v_ashrrev_i32_e32 v163, 31, v162
	v_lshlrev_b64 v[130:131], 11, v[150:151]
	v_add_u32_e32 v132, s0, v162
	v_lshl_add_u64 v[130:131], s[56:57], 0, v[130:131]
	v_lshlrev_b64 v[168:169], 1, v[162:163]
	s_waitcnt lgkmcnt(0)
	v_ashrrev_i32_e32 v133, 31, v132
	s_waitcnt lgkmcnt(0)
	s_barrier
	v_lshl_add_u64 v[130:131], v[130:131], 0, v[168:169]
	v_lshl_add_u64 v[148:149], v[132:133], 2, s[34:35]
	s_mov_b32 s17, 0x106000
	v_add_co_u32_e32 v130, vcc, s17, v148
	s_mov_b64 s[0:1], 0x106000
	s_nop 0
	v_addc_co_u32_e32 v131, vcc, 0, v149, vcc
	global_load_dwordx4 v[138:141], v[130:131], off
	v_lshl_add_u64 v[130:131], v[148:149], 0, s[0:1]
	global_load_dwordx4 v[142:145], v[130:131], off offset:64
	global_load_dwordx4 v[134:137], v[130:131], off offset:512
	s_nop 0
	global_load_dwordx4 v[130:133], v[130:131], off offset:576
	v_lshl_add_u32 v246, v150, 11, v168
	global_load_dwordx2 v[216:217], v246, s[56:57]
	global_load_dwordx2 v[218:219], v246, s[56:57] offset:32
	global_load_dwordx2 v[220:221], v246, s[56:57] offset:256
	global_load_dwordx2 v[222:223], v246, s[56:57] offset:288
	v_add_u32_e32 v247, 0x8000, v246
	global_load_dwordx2 v[224:225], v247, s[56:57]
	global_load_dwordx2 v[232:233], v247, s[56:57] offset:32
	global_load_dwordx2 v[234:235], v247, s[56:57] offset:256
	global_load_dwordx2 v[236:237], v247, s[56:57] offset:288
	v_add_u32_e32 v247, 0x10000, v246
	global_load_dwordx2 v[238:239], v247, s[56:57]
	global_load_dwordx2 v[240:241], v247, s[56:57] offset:32
	global_load_dwordx2 v[242:243], v247, s[56:57] offset:256
	global_load_dwordx2 v[244:245], v247, s[56:57] offset:288
	v_lshl_add_u32 v185, v152, 3, 0
	ds_read_b64 v[164:165], v185 offset:8192
	v_add_u32_e32 v152, 16, v150
	v_ashrrev_i32_e32 v153, 31, v152
	v_lshlrev_b64 v[166:167], 11, v[152:153]
	v_lshl_add_u64 v[166:167], s[56:57], 0, v[166:167]
	s_waitcnt lgkmcnt(0)
	v_pk_mul_f32 v[128:129], v[128:129], v[164:165] op_sel:[0,1]
	v_pk_mul_f32 v[126:127], v[126:127], v[164:165] op_sel:[0,1]
	v_pk_mul_f32 v[122:123], v[122:123], v[164:165] op_sel:[0,1]
	v_pk_mul_f32 v[124:125], v[124:125], v[164:165] op_sel:[0,1]
	v_pk_mul_f32 v[172:173], v[118:119], v[164:165] op_sel:[0,1]
	v_pk_mul_f32 v[174:175], v[120:121], v[164:165] op_sel:[0,1]
	v_pk_mul_f32 v[114:115], v[114:115], v[164:165] op_sel:[0,1]
	v_pk_mul_f32 v[116:117], v[116:117], v[164:165] op_sel:[0,1]
	v_lshl_add_u64 v[166:167], v[166:167], 0, v[168:169]
	s_waitcnt vmcnt(11)
	v_lshlrev_b32_e32 v118, 16, v216
	v_and_b32_e32 v119, 0xffff0000, v216
	v_lshlrev_b32_e32 v120, 16, v217
	v_and_b32_e32 v121, 0xffff0000, v217
	s_waitcnt vmcnt(10)
	v_lshlrev_b32_e32 v154, 16, v218
	v_and_b32_e32 v155, 0xffff0000, v218
	v_lshlrev_b32_e32 v156, 16, v219
	v_and_b32_e32 v157, 0xffff0000, v219
	s_waitcnt vmcnt(9)
	v_lshlrev_b32_e32 v164, 16, v220
	v_and_b32_e32 v165, 0xffff0000, v220
	v_lshlrev_b32_e32 v158, 16, v221
	v_and_b32_e32 v159, 0xffff0000, v221
	s_waitcnt vmcnt(8)
	v_lshlrev_b32_e32 v176, 16, v222
	v_and_b32_e32 v177, 0xffff0000, v222
	v_lshlrev_b32_e32 v160, 16, v223
	v_and_b32_e32 v161, 0xffff0000, v223
	v_pk_fma_f32 v[118:119], v[138:139], v[126:127], v[118:119]
	v_pk_fma_f32 v[120:121], v[140:141], v[128:129], v[120:121]
	v_pk_fma_f32 v[124:125], v[144:145], v[124:125], v[156:157]
	v_pk_fma_f32 v[122:123], v[142:143], v[122:123], v[154:155]
	v_pk_fma_f32 v[128:129], v[136:137], v[174:175], v[158:159]
	v_pk_fma_f32 v[126:127], v[134:135], v[172:173], v[164:165]
	v_pk_fma_f32 v[116:117], v[132:133], v[116:117], v[160:161]
	v_pk_fma_f32 v[114:115], v[130:131], v[114:115], v[176:177]
	v_add_u32_e32 v154, 32, v150
	v_add_u32_e32 v247, 0x18000, v246
	global_load_dwordx2 v[216:217], v247, s[56:57]
	global_load_dwordx2 v[218:219], v247, s[56:57] offset:32
	global_load_dwordx2 v[220:221], v247, s[56:57] offset:256
	global_load_dwordx2 v[222:223], v247, s[56:57] offset:288
	ds_read_b64 v[166:167], v185 offset:8320
	v_ashrrev_i32_e32 v155, 31, v154
	v_lshlrev_b64 v[172:173], 11, v[154:155]
	v_lshl_add_u64 v[172:173], s[56:57], 0, v[172:173]
	v_lshl_add_u64 v[172:173], v[172:173], 0, v[168:169]
	s_waitcnt lgkmcnt(0)
	v_pk_mul_f32 v[110:111], v[110:111], v[166:167] op_sel:[0,1]
	v_pk_mul_f32 v[112:113], v[112:113], v[166:167] op_sel:[0,1]
	v_pk_mul_f32 v[106:107], v[106:107], v[166:167] op_sel:[0,1]
	v_pk_mul_f32 v[108:109], v[108:109], v[166:167] op_sel:[0,1]
	v_pk_mul_f32 v[102:103], v[102:103], v[166:167] op_sel:[0,1]
	v_pk_mul_f32 v[104:105], v[104:105], v[166:167] op_sel:[0,1]
	v_pk_mul_f32 v[98:99], v[98:99], v[166:167] op_sel:[0,1]
	v_pk_mul_f32 v[100:101], v[100:101], v[166:167] op_sel:[0,1]
	v_add_f32_e32 v195, v126, v127
	v_add_f32_e32 v205, v128, v129
	v_mov_b32_e32 v194, v114
	v_mov_b32_e32 v204, v115
	v_mov_b32_e32 v206, v117
	s_waitcnt vmcnt(11)
	v_lshlrev_b32_e32 v166, 16, v224
	v_and_b32_e32 v167, 0xffff0000, v224
	v_lshlrev_b32_e32 v156, 16, v225
	v_and_b32_e32 v157, 0xffff0000, v225
	s_waitcnt vmcnt(10)
	v_lshlrev_b32_e32 v174, 16, v232
	v_and_b32_e32 v175, 0xffff0000, v232
	v_lshlrev_b32_e32 v158, 16, v233
	v_and_b32_e32 v159, 0xffff0000, v233
	s_waitcnt vmcnt(9)
	v_lshlrev_b32_e32 v176, 16, v234
	v_and_b32_e32 v177, 0xffff0000, v234
	v_lshlrev_b32_e32 v160, 16, v235
	v_and_b32_e32 v161, 0xffff0000, v235
	s_waitcnt vmcnt(8)
	v_lshlrev_b32_e32 v178, 16, v236
	v_and_b32_e32 v179, 0xffff0000, v236
	v_lshlrev_b32_e32 v164, 16, v237
	v_and_b32_e32 v165, 0xffff0000, v237
	v_pk_fma_f32 v[112:113], v[140:141], v[112:113], v[156:157]
	v_pk_fma_f32 v[110:111], v[138:139], v[110:111], v[166:167]
	v_pk_fma_f32 v[108:109], v[144:145], v[108:109], v[158:159]
	v_pk_fma_f32 v[106:107], v[142:143], v[106:107], v[174:175]
	v_pk_fma_f32 v[104:105], v[136:137], v[104:105], v[160:161]
	v_pk_fma_f32 v[102:103], v[134:135], v[102:103], v[176:177]
	v_pk_fma_f32 v[100:101], v[132:133], v[100:101], v[164:165]
	v_pk_fma_f32 v[98:99], v[130:131], v[98:99], v[178:179]
	v_add_u32_e32 v156, 48, v150
	v_add_u32_e32 v247, 0x40000, v246
	global_load_dwordx2 v[224:225], v247, s[56:57]
	global_load_dwordx2 v[232:233], v247, s[56:57] offset:32
	global_load_dwordx2 v[234:235], v247, s[56:57] offset:256
	global_load_dwordx2 v[236:237], v247, s[56:57] offset:288
	ds_read_b64 v[172:173], v185 offset:8448
	v_ashrrev_i32_e32 v157, 31, v156
	v_lshlrev_b64 v[174:175], 11, v[156:157]
	v_lshl_add_u64 v[174:175], s[56:57], 0, v[174:175]
	v_lshl_add_u64 v[174:175], v[174:175], 0, v[168:169]
	s_waitcnt lgkmcnt(0)
	v_pk_mul_f32 v[94:95], v[94:95], v[172:173] op_sel:[0,1]
	v_pk_mul_f32 v[96:97], v[96:97], v[172:173] op_sel:[0,1]
	v_pk_mul_f32 v[90:91], v[90:91], v[172:173] op_sel:[0,1]
	v_pk_mul_f32 v[92:93], v[92:93], v[172:173] op_sel:[0,1]
	v_pk_mul_f32 v[86:87], v[86:87], v[172:173] op_sel:[0,1]
	v_pk_mul_f32 v[88:89], v[88:89], v[172:173] op_sel:[0,1]
	v_pk_mul_f32 v[82:83], v[82:83], v[172:173] op_sel:[0,1]
	v_pk_mul_f32 v[84:85], v[84:85], v[172:173] op_sel:[0,1]
	s_waitcnt vmcnt(11)
	v_lshlrev_b32_e32 v172, 16, v238
	v_and_b32_e32 v173, 0xffff0000, v238
	v_lshlrev_b32_e32 v158, 16, v239
	v_and_b32_e32 v159, 0xffff0000, v239
	s_waitcnt vmcnt(10)
	v_lshlrev_b32_e32 v176, 16, v240
	v_and_b32_e32 v177, 0xffff0000, v240
	v_lshlrev_b32_e32 v160, 16, v241
	v_and_b32_e32 v161, 0xffff0000, v241
	s_waitcnt vmcnt(9)
	v_lshlrev_b32_e32 v178, 16, v242
	v_and_b32_e32 v179, 0xffff0000, v242
	v_lshlrev_b32_e32 v164, 16, v243
	v_and_b32_e32 v165, 0xffff0000, v243
	s_waitcnt vmcnt(8)
	v_lshlrev_b32_e32 v180, 16, v244
	v_and_b32_e32 v181, 0xffff0000, v244
	v_lshlrev_b32_e32 v166, 16, v245
	v_and_b32_e32 v167, 0xffff0000, v245
	v_pk_fma_f32 v[96:97], v[140:141], v[96:97], v[158:159]
	v_pk_fma_f32 v[94:95], v[138:139], v[94:95], v[172:173]
	v_pk_fma_f32 v[92:93], v[144:145], v[92:93], v[160:161]
	v_pk_fma_f32 v[90:91], v[142:143], v[90:91], v[176:177]
	v_pk_fma_f32 v[88:89], v[136:137], v[88:89], v[164:165]
	v_pk_fma_f32 v[86:87], v[134:135], v[86:87], v[178:179]
	v_pk_fma_f32 v[84:85], v[132:133], v[84:85], v[166:167]
	v_pk_fma_f32 v[82:83], v[130:131], v[82:83], v[180:181]
	v_add_u32_e32 v158, 0x80, v150
	v_add_u32_e32 v247, 0x48000, v246
	global_load_dwordx2 v[238:239], v247, s[56:57]
	global_load_dwordx2 v[240:241], v247, s[56:57] offset:32
	global_load_dwordx2 v[242:243], v247, s[56:57] offset:256
	global_load_dwordx2 v[244:245], v247, s[56:57] offset:288
	ds_read_b64 v[174:175], v185 offset:8576
	v_ashrrev_i32_e32 v159, 31, v158
	v_lshlrev_b64 v[176:177], 11, v[158:159]
	v_lshl_add_u64 v[176:177], s[56:57], 0, v[176:177]
	v_lshl_add_u64 v[176:177], v[176:177], 0, v[168:169]
	s_waitcnt lgkmcnt(0)
	v_pk_mul_f32 v[78:79], v[78:79], v[174:175] op_sel:[0,1]
	v_pk_mul_f32 v[80:81], v[80:81], v[174:175] op_sel:[0,1]
	v_pk_mul_f32 v[74:75], v[74:75], v[174:175] op_sel:[0,1]
	v_pk_mul_f32 v[76:77], v[76:77], v[174:175] op_sel:[0,1]
	v_pk_mul_f32 v[70:71], v[70:71], v[174:175] op_sel:[0,1]
	v_pk_mul_f32 v[72:73], v[72:73], v[174:175] op_sel:[0,1]
	v_pk_mul_f32 v[66:67], v[66:67], v[174:175] op_sel:[0,1]
	v_pk_mul_f32 v[68:69], v[68:69], v[174:175] op_sel:[0,1]
	s_waitcnt vmcnt(11)
	v_lshlrev_b32_e32 v174, 16, v216
	v_and_b32_e32 v175, 0xffff0000, v216
	v_lshlrev_b32_e32 v160, 16, v217
	v_and_b32_e32 v161, 0xffff0000, v217
	s_waitcnt vmcnt(10)
	v_lshlrev_b32_e32 v178, 16, v218
	v_and_b32_e32 v179, 0xffff0000, v218
	v_lshlrev_b32_e32 v164, 16, v219
	v_and_b32_e32 v165, 0xffff0000, v219
	s_waitcnt vmcnt(9)
	v_lshlrev_b32_e32 v180, 16, v220
	v_and_b32_e32 v181, 0xffff0000, v220
	v_lshlrev_b32_e32 v166, 16, v221
	v_and_b32_e32 v167, 0xffff0000, v221
	s_waitcnt vmcnt(8)
	v_lshlrev_b32_e32 v188, 16, v222
	v_and_b32_e32 v189, 0xffff0000, v222
	v_lshlrev_b32_e32 v172, 16, v223
	v_and_b32_e32 v173, 0xffff0000, v223
	v_pk_fma_f32 v[80:81], v[140:141], v[80:81], v[160:161]
	v_pk_fma_f32 v[78:79], v[138:139], v[78:79], v[174:175]
	v_pk_fma_f32 v[76:77], v[144:145], v[76:77], v[164:165]
	v_pk_fma_f32 v[74:75], v[142:143], v[74:75], v[178:179]
	v_pk_fma_f32 v[72:73], v[136:137], v[72:73], v[166:167]
	v_pk_fma_f32 v[70:71], v[134:135], v[70:71], v[180:181]
	v_pk_fma_f32 v[68:69], v[132:133], v[68:69], v[172:173]
	v_pk_fma_f32 v[66:67], v[130:131], v[66:67], v[188:189]
	v_add_u32_e32 v160, 0x90, v150
	v_add_u32_e32 v247, 0x50000, v246
	global_load_dwordx2 v[216:217], v247, s[56:57]
	global_load_dwordx2 v[218:219], v247, s[56:57] offset:32
	global_load_dwordx2 v[220:221], v247, s[56:57] offset:256
	global_load_dwordx2 v[222:223], v247, s[56:57] offset:288
	ds_read_b64 v[176:177], v185 offset:9216
	v_ashrrev_i32_e32 v161, 31, v160
	v_lshlrev_b64 v[178:179], 11, v[160:161]
	v_lshl_add_u64 v[178:179], s[56:57], 0, v[178:179]
	v_lshl_add_u64 v[178:179], v[178:179], 0, v[168:169]
	s_waitcnt lgkmcnt(0)
	v_pk_mul_f32 v[62:63], v[62:63], v[176:177] op_sel:[0,1]
	v_pk_mul_f32 v[64:65], v[64:65], v[176:177] op_sel:[0,1]
	v_pk_mul_f32 v[58:59], v[58:59], v[176:177] op_sel:[0,1]
	v_pk_mul_f32 v[60:61], v[60:61], v[176:177] op_sel:[0,1]
	v_pk_mul_f32 v[54:55], v[54:55], v[176:177] op_sel:[0,1]
	v_pk_mul_f32 v[56:57], v[56:57], v[176:177] op_sel:[0,1]
	v_pk_mul_f32 v[50:51], v[50:51], v[176:177] op_sel:[0,1]
	v_pk_mul_f32 v[52:53], v[52:53], v[176:177] op_sel:[0,1]
	s_waitcnt vmcnt(11)
	v_lshlrev_b32_e32 v176, 16, v224
	v_and_b32_e32 v177, 0xffff0000, v224
	v_lshlrev_b32_e32 v164, 16, v225
	v_and_b32_e32 v165, 0xffff0000, v225
	s_waitcnt vmcnt(10)
	v_lshlrev_b32_e32 v180, 16, v232
	v_and_b32_e32 v181, 0xffff0000, v232
	v_lshlrev_b32_e32 v166, 16, v233
	v_and_b32_e32 v167, 0xffff0000, v233
	s_waitcnt vmcnt(9)
	v_lshlrev_b32_e32 v188, 16, v234
	v_and_b32_e32 v189, 0xffff0000, v234
	v_lshlrev_b32_e32 v172, 16, v235
	v_and_b32_e32 v173, 0xffff0000, v235
	s_waitcnt vmcnt(8)
	v_lshlrev_b32_e32 v190, 16, v236
	v_and_b32_e32 v191, 0xffff0000, v236
	v_lshlrev_b32_e32 v174, 16, v237
	v_and_b32_e32 v175, 0xffff0000, v237
	v_pk_fma_f32 v[64:65], v[140:141], v[64:65], v[164:165]
	v_pk_fma_f32 v[62:63], v[138:139], v[62:63], v[176:177]
	v_pk_fma_f32 v[60:61], v[144:145], v[60:61], v[166:167]
	v_pk_fma_f32 v[58:59], v[142:143], v[58:59], v[180:181]
	v_pk_fma_f32 v[56:57], v[136:137], v[56:57], v[172:173]
	v_pk_fma_f32 v[54:55], v[134:135], v[54:55], v[188:189]
	v_pk_fma_f32 v[52:53], v[132:133], v[52:53], v[174:175]
	v_pk_fma_f32 v[50:51], v[130:131], v[50:51], v[190:191]
	v_add_u32_e32 v164, 0xa0, v150
	v_add_u32_e32 v247, 0x58000, v246
	global_load_dwordx2 v[224:225], v247, s[56:57]
	global_load_dwordx2 v[232:233], v247, s[56:57] offset:32
	global_load_dwordx2 v[234:235], v247, s[56:57] offset:256
	global_load_dwordx2 v[236:237], v247, s[56:57] offset:288
	ds_read_b64 v[178:179], v185 offset:9344
	v_ashrrev_i32_e32 v165, 31, v164
	v_lshlrev_b64 v[180:181], 11, v[164:165]
	v_lshl_add_u64 v[180:181], s[56:57], 0, v[180:181]
	v_lshl_add_u64 v[180:181], v[180:181], 0, v[168:169]
	s_waitcnt lgkmcnt(0)
	v_pk_mul_f32 v[46:47], v[46:47], v[178:179] op_sel:[0,1]
	v_pk_mul_f32 v[48:49], v[48:49], v[178:179] op_sel:[0,1]
	v_pk_mul_f32 v[42:43], v[42:43], v[178:179] op_sel:[0,1]
	v_pk_mul_f32 v[44:45], v[44:45], v[178:179] op_sel:[0,1]
	v_pk_mul_f32 v[38:39], v[38:39], v[178:179] op_sel:[0,1]
	v_pk_mul_f32 v[40:41], v[40:41], v[178:179] op_sel:[0,1]
	v_pk_mul_f32 v[34:35], v[34:35], v[178:179] op_sel:[0,1]
	v_pk_mul_f32 v[36:37], v[36:37], v[178:179] op_sel:[0,1]
	s_waitcnt vmcnt(11)
	v_lshlrev_b32_e32 v178, 16, v238
	v_and_b32_e32 v179, 0xffff0000, v238
	v_lshlrev_b32_e32 v166, 16, v239
	v_and_b32_e32 v167, 0xffff0000, v239
	s_waitcnt vmcnt(10)
	v_lshlrev_b32_e32 v188, 16, v240
	v_and_b32_e32 v189, 0xffff0000, v240
	v_lshlrev_b32_e32 v172, 16, v241
	v_and_b32_e32 v173, 0xffff0000, v241
	s_waitcnt vmcnt(9)
	v_lshlrev_b32_e32 v190, 16, v242
	v_and_b32_e32 v191, 0xffff0000, v242
	v_lshlrev_b32_e32 v174, 16, v243
	v_and_b32_e32 v175, 0xffff0000, v243
	s_waitcnt vmcnt(8)
	v_lshlrev_b32_e32 v192, 16, v244
	v_and_b32_e32 v193, 0xffff0000, v244
	v_lshlrev_b32_e32 v176, 16, v245
	v_and_b32_e32 v177, 0xffff0000, v245
	v_pk_fma_f32 v[48:49], v[140:141], v[48:49], v[166:167]
	v_pk_fma_f32 v[46:47], v[138:139], v[46:47], v[178:179]
	v_pk_fma_f32 v[44:45], v[144:145], v[44:45], v[172:173]
	v_pk_fma_f32 v[42:43], v[142:143], v[42:43], v[188:189]
	v_pk_fma_f32 v[40:41], v[136:137], v[40:41], v[174:175]
	v_pk_fma_f32 v[38:39], v[134:135], v[38:39], v[190:191]
	v_pk_fma_f32 v[36:37], v[132:133], v[36:37], v[176:177]
	v_pk_fma_f32 v[34:35], v[130:131], v[34:35], v[192:193]
	v_add_u32_e32 v166, 0xb0, v150
	ds_read_b64 v[196:197], v185 offset:9472
	v_ashrrev_i32_e32 v167, 31, v166
	v_lshlrev_b64 v[180:181], 11, v[166:167]
	v_lshl_add_u64 v[180:181], s[56:57], 0, v[180:181]
	v_lshl_add_u64 v[168:169], v[180:181], 0, v[168:169]
	v_mov_b32_e32 v180, v119
	v_mov_b32_e32 v181, v120
	v_mov_b32_e32 v188, v118
	v_mov_b32_e32 v189, v121
	v_mov_b32_e32 v190, v123
	v_mov_b32_e32 v191, v124
	v_mov_b32_e32 v192, v122
	v_mov_b32_e32 v193, v125
	s_waitcnt lgkmcnt(0)
	v_pk_mul_f32 v[30:31], v[30:31], v[196:197] op_sel:[0,1]
	v_pk_mul_f32 v[32:33], v[32:33], v[196:197] op_sel:[0,1]
	v_pk_mul_f32 v[26:27], v[26:27], v[196:197] op_sel:[0,1]
	v_pk_mul_f32 v[28:29], v[28:29], v[196:197] op_sel:[0,1]
	v_pk_mul_f32 v[22:23], v[22:23], v[196:197] op_sel:[0,1]
	v_pk_mul_f32 v[24:25], v[24:25], v[196:197] op_sel:[0,1]
	v_pk_mul_f32 v[18:19], v[18:19], v[196:197] op_sel:[0,1]
	v_pk_mul_f32 v[20:21], v[20:21], v[196:197] op_sel:[0,1]
	s_waitcnt vmcnt(7)
	v_lshlrev_b32_e32 v196, 16, v216
	v_and_b32_e32 v197, 0xffff0000, v216
	v_lshlrev_b32_e32 v172, 16, v217
	v_and_b32_e32 v173, 0xffff0000, v217
	s_waitcnt vmcnt(5)
	v_lshlrev_b32_e32 v210, 16, v220
	v_and_b32_e32 v211, 0xffff0000, v220
	v_lshlrev_b32_e32 v176, 16, v221
	v_and_b32_e32 v177, 0xffff0000, v221
	v_pk_fma_f32 v[32:33], v[140:141], v[32:33], v[172:173]
	v_pk_fma_f32 v[24:25], v[136:137], v[24:25], v[176:177]
	v_pk_add_f32 v[172:173], v[180:181], v[188:189]
	v_pk_add_f32 v[176:177], v[190:191], v[192:193]
	v_add_f32_e32 v188, v172, v173
	v_pk_add_f32 v[172:173], v[176:177], v[176:177] op_sel_hi:[0,1]
	s_waitcnt vmcnt(6)
	v_lshlrev_b32_e32 v208, 16, v218
	v_and_b32_e32 v209, 0xffff0000, v218
	v_lshlrev_b32_e32 v174, 16, v219
	v_and_b32_e32 v175, 0xffff0000, v219
	s_waitcnt vmcnt(4)
	v_lshlrev_b32_e32 v212, 16, v222
	v_and_b32_e32 v213, 0xffff0000, v222
	v_lshlrev_b32_e32 v178, 16, v223
	v_and_b32_e32 v179, 0xffff0000, v223
	v_add_f32_e32 v207, 0, v188
	v_mov_b32_e32 v172, v116
	v_pk_fma_f32 v[30:31], v[138:139], v[30:31], v[196:197]
	v_pk_fma_f32 v[28:29], v[144:145], v[28:29], v[174:175]
	v_pk_fma_f32 v[26:27], v[142:143], v[26:27], v[208:209]
	v_pk_fma_f32 v[22:23], v[134:135], v[22:23], v[210:211]
	v_pk_fma_f32 v[20:21], v[132:133], v[20:21], v[178:179]
	v_pk_fma_f32 v[18:19], v[130:131], v[18:19], v[212:213]
	v_pk_add_f32 v[178:179], v[194:195], v[204:205]
	v_pk_add_f32 v[172:173], v[172:173], v[206:207]
	v_pk_add_f32 v[172:173], v[178:179], v[172:173]
	v_add_f32_e32 v168, v172, v173
	v_mov_b32_e32 v169, v168
	s_nop 1
	v_permlane16_swap_b32_e32 v168, v169
	s_waitcnt lgkmcnt(0)
	v_add_f32_e32 v168, v168, v169
	v_mov_b32_e32 v169, v168
	s_nop 1
	v_permlane32_swap_b32_e32 v168, v169
	s_waitcnt lgkmcnt(0)
	v_add_f32_e32 v168, v168, v169
	v_fmamk_f32 v172, v168, 0xbc800000, v121
	v_fmamk_f32 v188, v168, 0xbc800000, v119
	v_fmamk_f32 v190, v168, 0xbc800000, v125
	v_fmamk_f32 v192, v168, 0xbc800000, v123
	v_fmamk_f32 v169, v168, 0xbc800000, v120
	v_fmamk_f32 v173, v168, 0xbc800000, v118
	v_fmamk_f32 v189, v168, 0xbc800000, v124
	v_fmamk_f32 v191, v168, 0xbc800000, v122
	v_fmamk_f32 v194, v168, 0xbc800000, v129
	v_fmamk_f32 v196, v168, 0xbc800000, v127
	v_mul_f32_e32 v188, v188, v188
	v_mul_f32_e32 v172, v172, v172
	v_mul_f32_e32 v192, v192, v192
	v_mul_f32_e32 v190, v190, v190
	v_fmamk_f32 v193, v168, 0xbc800000, v128
	v_fmamk_f32 v195, v168, 0xbc800000, v126
	v_fmamk_f32 v200, v168, 0xbc800000, v117
	v_fmamk_f32 v205, v168, 0xbc800000, v115
	v_mul_f32_e32 v196, v196, v196
	v_mul_f32_e32 v194, v194, v194
	v_fmac_f32_e32 v188, v173, v173
	v_fmac_f32_e32 v172, v169, v169
	v_fmac_f32_e32 v192, v191, v191
	v_fmac_f32_e32 v190, v189, v189
	v_fmamk_f32 v197, v168, 0xbc800000, v116
	v_fmamk_f32 v204, v168, 0xbc800000, v114
	v_mul_f32_e32 v205, v205, v205
	v_mul_f32_e32 v200, v200, v200
	v_fmac_f32_e32 v196, v195, v195
	v_fmac_f32_e32 v194, v193, v193
	v_add_f32_e32 v169, v188, v172
	v_add_f32_e32 v172, v192, v190
	v_fmac_f32_e32 v205, v204, v204
	v_fmac_f32_e32 v200, v197, v197
	v_add_f32_e32 v173, v196, v194
	v_add_f32_e32 v169, v169, v172
	v_add_f32_e32 v188, v205, v200
	v_add_f32_e32 v169, v173, v169
	v_add_f32_e32 v169, v188, v169
	v_mov_b32_e32 v172, v169
	s_nop 1
	v_permlane16_swap_b32_e32 v169, v172
	ds_read_b64 v[188:189], v185 offset:9600
	s_waitcnt lgkmcnt(1)
	v_add_f32_e32 v169, v169, v172
	ds_bpermute_b32 v172, v202, v169
	s_waitcnt lgkmcnt(1)
	v_pk_mul_f32 v[14:15], v[14:15], v[188:189] op_sel:[0,1]
	v_pk_mul_f32 v[16:17], v[16:17], v[188:189] op_sel:[0,1]
	v_pk_mul_f32 v[10:11], v[10:11], v[188:189] op_sel:[0,1]
	v_pk_mul_f32 v[12:13], v[12:13], v[188:189] op_sel:[0,1]
	v_pk_mul_f32 v[6:7], v[6:7], v[188:189] op_sel:[0,1]
	v_pk_mul_f32 v[8:9], v[8:9], v[188:189] op_sel:[0,1]
	v_pk_mul_f32 v[2:3], v[2:3], v[188:189] op_sel:[0,1]
	v_pk_mul_f32 v[4:5], v[4:5], v[188:189] op_sel:[0,1]
	s_waitcnt vmcnt(3)
	v_lshlrev_b32_e32 v188, 16, v224
	v_and_b32_e32 v189, 0xffff0000, v224
	v_lshlrev_b32_e32 v174, 16, v225
	v_and_b32_e32 v175, 0xffff0000, v225
	s_waitcnt vmcnt(2)
	v_lshlrev_b32_e32 v190, 16, v232
	v_and_b32_e32 v191, 0xffff0000, v232
	v_lshlrev_b32_e32 v180, 16, v233
	v_and_b32_e32 v181, 0xffff0000, v233
	s_waitcnt vmcnt(1)
	v_lshlrev_b32_e32 v192, 16, v234
	v_and_b32_e32 v193, 0xffff0000, v234
	v_lshlrev_b32_e32 v176, 16, v235
	v_and_b32_e32 v177, 0xffff0000, v235
	s_waitcnt vmcnt(0)
	v_lshlrev_b32_e32 v194, 16, v236
	v_and_b32_e32 v195, 0xffff0000, v236
	v_lshlrev_b32_e32 v178, 16, v237
	v_and_b32_e32 v179, 0xffff0000, v237
	v_pk_fma_f32 v[16:17], v[140:141], v[16:17], v[174:175]
	v_pk_fma_f32 v[14:15], v[138:139], v[14:15], v[188:189]
	v_pk_fma_f32 v[12:13], v[144:145], v[12:13], v[180:181]
	v_pk_fma_f32 v[10:11], v[142:143], v[10:11], v[190:191]
	v_pk_fma_f32 v[8:9], v[136:137], v[8:9], v[176:177]
	v_pk_fma_f32 v[6:7], v[134:135], v[6:7], v[192:193]
	v_pk_fma_f32 v[4:5], v[132:133], v[4:5], v[178:179]
	v_pk_fma_f32 v[2:3], v[130:131], v[2:3], v[194:195]
	s_nop 0
	s_and_saveexec_b64 s[0:1], s[6:7]
	s_cbranch_execz .LBB0_898
	s_lshl_b32 s17, s27, 11
	s_add_i32 s17, s28, s17
	v_mul_f32_e32 v130, 0x3c800000, v168
	s_waitcnt lgkmcnt(0)
	v_add_f32_e32 v131, v169, v172
	v_lshl_add_u32 v132, v170, 5, s17
	ds_write_b64 v132, v[130:131]

.LBB0_1491:
	s_or_b64 exec, exec, s[22:23]
	s_lshl_b32 s0, s40, 5
	s_lshl_b32 s1, s18, 8
	s_or_b32 s0, s1, s0
	v_lshrrev_b32_e32 v130, 2, v148
	v_and_or_b32 v162, v130, 12, s0
	v_add_u32_e32 v150, s19, v152
	s_lshl_b32 s0, s16, 5
	v_ashrrev_i32_e32 v151, 31, v150
	s_and_b32 s0, s0, 0xfffffc00
	v_ashrrev_i32_e32 v163, 31, v162
	v_lshlrev_b64 v[130:131], 11, v[150:151]
	v_add_u32_e32 v132, s0, v162
	v_lshl_add_u64 v[130:131], s[94:95], 0, v[130:131]
	v_lshlrev_b64 v[168:169], 1, v[162:163]
	s_waitcnt lgkmcnt(0)
	v_ashrrev_i32_e32 v133, 31, v132
	s_waitcnt lgkmcnt(0)
	s_barrier
	v_lshl_add_u64 v[130:131], v[130:131], 0, v[168:169]
	v_lshl_add_u64 v[148:149], v[132:133], 2, s[34:35]
	s_mov_b32 s19, 0x10c000
	v_add_co_u32_e32 v130, vcc, s19, v148
	s_mov_b64 s[0:1], 0x10c000
	s_nop 0
	v_addc_co_u32_e32 v131, vcc, 0, v149, vcc
	global_load_dwordx4 v[138:141], v[130:131], off
	v_lshl_add_u64 v[130:131], v[148:149], 0, s[0:1]
	global_load_dwordx4 v[142:145], v[130:131], off offset:64
	global_load_dwordx4 v[134:137], v[130:131], off offset:512
	s_nop 0
	global_load_dwordx4 v[130:133], v[130:131], off offset:576
	v_lshl_add_u32 v246, v150, 11, v168
	global_load_dwordx2 v[216:217], v246, s[94:95]
	global_load_dwordx2 v[218:219], v246, s[94:95] offset:32
	global_load_dwordx2 v[220:221], v246, s[94:95] offset:256
	global_load_dwordx2 v[222:223], v246, s[94:95] offset:288
	v_add_u32_e32 v247, 0x8000, v246
	global_load_dwordx2 v[224:225], v247, s[94:95]
	global_load_dwordx2 v[232:233], v247, s[94:95] offset:32
	global_load_dwordx2 v[234:235], v247, s[94:95] offset:256
	global_load_dwordx2 v[236:237], v247, s[94:95] offset:288
	v_add_u32_e32 v247, 0x10000, v246
	global_load_dwordx2 v[238:239], v247, s[94:95]
	global_load_dwordx2 v[240:241], v247, s[94:95] offset:32
	global_load_dwordx2 v[242:243], v247, s[94:95] offset:256
	global_load_dwordx2 v[244:245], v247, s[94:95] offset:288
	v_lshl_add_u32 v183, v152, 3, 0
	ds_read_b64 v[164:165], v183 offset:8192
	v_add_u32_e32 v152, 16, v150
	v_ashrrev_i32_e32 v153, 31, v152
	v_lshlrev_b64 v[166:167], 11, v[152:153]
	v_lshl_add_u64 v[166:167], s[94:95], 0, v[166:167]
	s_waitcnt lgkmcnt(0)
	v_pk_mul_f32 v[128:129], v[128:129], v[164:165] op_sel:[0,1]
	v_pk_mul_f32 v[126:127], v[126:127], v[164:165] op_sel:[0,1]
	v_pk_mul_f32 v[122:123], v[122:123], v[164:165] op_sel:[0,1]
	v_pk_mul_f32 v[124:125], v[124:125], v[164:165] op_sel:[0,1]
	v_pk_mul_f32 v[172:173], v[118:119], v[164:165] op_sel:[0,1]
	v_pk_mul_f32 v[174:175], v[120:121], v[164:165] op_sel:[0,1]
	v_pk_mul_f32 v[114:115], v[114:115], v[164:165] op_sel:[0,1]
	v_pk_mul_f32 v[116:117], v[116:117], v[164:165] op_sel:[0,1]
	v_lshl_add_u64 v[166:167], v[166:167], 0, v[168:169]
	s_waitcnt vmcnt(11)
	v_lshlrev_b32_e32 v118, 16, v216
	v_and_b32_e32 v119, 0xffff0000, v216
	v_lshlrev_b32_e32 v120, 16, v217
	v_and_b32_e32 v121, 0xffff0000, v217
	s_waitcnt vmcnt(10)
	v_lshlrev_b32_e32 v154, 16, v218
	v_and_b32_e32 v155, 0xffff0000, v218
	v_lshlrev_b32_e32 v156, 16, v219
	v_and_b32_e32 v157, 0xffff0000, v219
	s_waitcnt vmcnt(9)
	v_lshlrev_b32_e32 v164, 16, v220
	v_and_b32_e32 v165, 0xffff0000, v220
	v_lshlrev_b32_e32 v158, 16, v221
	v_and_b32_e32 v159, 0xffff0000, v221
	s_waitcnt vmcnt(8)
	v_lshlrev_b32_e32 v176, 16, v222
	v_and_b32_e32 v177, 0xffff0000, v222
	v_lshlrev_b32_e32 v160, 16, v223
	v_and_b32_e32 v161, 0xffff0000, v223
	v_pk_fma_f32 v[118:119], v[138:139], v[126:127], v[118:119]
	v_pk_fma_f32 v[120:121], v[140:141], v[128:129], v[120:121]
	v_pk_fma_f32 v[124:125], v[144:145], v[124:125], v[156:157]
	v_pk_fma_f32 v[122:123], v[142:143], v[122:123], v[154:155]
	v_pk_fma_f32 v[128:129], v[136:137], v[174:175], v[158:159]
	v_pk_fma_f32 v[126:127], v[134:135], v[172:173], v[164:165]
	v_pk_fma_f32 v[116:117], v[132:133], v[116:117], v[160:161]
	v_pk_fma_f32 v[114:115], v[130:131], v[114:115], v[176:177]
	v_add_u32_e32 v154, 32, v150
	v_add_u32_e32 v247, 0x18000, v246
	global_load_dwordx2 v[216:217], v247, s[94:95]
	global_load_dwordx2 v[218:219], v247, s[94:95] offset:32
	global_load_dwordx2 v[220:221], v247, s[94:95] offset:256
	global_load_dwordx2 v[222:223], v247, s[94:95] offset:288
	ds_read_b64 v[166:167], v183 offset:8320
	v_ashrrev_i32_e32 v155, 31, v154
	v_lshlrev_b64 v[172:173], 11, v[154:155]
	v_lshl_add_u64 v[172:173], s[94:95], 0, v[172:173]
	v_lshl_add_u64 v[172:173], v[172:173], 0, v[168:169]
	s_waitcnt lgkmcnt(0)
	v_pk_mul_f32 v[110:111], v[110:111], v[166:167] op_sel:[0,1]
	v_pk_mul_f32 v[112:113], v[112:113], v[166:167] op_sel:[0,1]
	v_pk_mul_f32 v[106:107], v[106:107], v[166:167] op_sel:[0,1]
	v_pk_mul_f32 v[108:109], v[108:109], v[166:167] op_sel:[0,1]
	v_pk_mul_f32 v[102:103], v[102:103], v[166:167] op_sel:[0,1]
	v_pk_mul_f32 v[104:105], v[104:105], v[166:167] op_sel:[0,1]
	v_pk_mul_f32 v[98:99], v[98:99], v[166:167] op_sel:[0,1]
	v_pk_mul_f32 v[100:101], v[100:101], v[166:167] op_sel:[0,1]
	v_add_f32_e32 v193, v126, v127
	v_add_f32_e32 v197, v128, v129
	v_mov_b32_e32 v192, v114
	v_mov_b32_e32 v196, v115
	v_mov_b32_e32 v198, v117
	s_waitcnt vmcnt(11)
	v_lshlrev_b32_e32 v166, 16, v224
	v_and_b32_e32 v167, 0xffff0000, v224
	v_lshlrev_b32_e32 v156, 16, v225
	v_and_b32_e32 v157, 0xffff0000, v225
	s_waitcnt vmcnt(10)
	v_lshlrev_b32_e32 v174, 16, v232
	v_and_b32_e32 v175, 0xffff0000, v232
	v_lshlrev_b32_e32 v158, 16, v233
	v_and_b32_e32 v159, 0xffff0000, v233
	s_waitcnt vmcnt(9)
	v_lshlrev_b32_e32 v176, 16, v234
	v_and_b32_e32 v177, 0xffff0000, v234
	v_lshlrev_b32_e32 v160, 16, v235
	v_and_b32_e32 v161, 0xffff0000, v235
	s_waitcnt vmcnt(8)
	v_lshlrev_b32_e32 v178, 16, v236
	v_and_b32_e32 v179, 0xffff0000, v236
	v_lshlrev_b32_e32 v164, 16, v237
	v_and_b32_e32 v165, 0xffff0000, v237
	v_pk_fma_f32 v[112:113], v[140:141], v[112:113], v[156:157]
	v_pk_fma_f32 v[110:111], v[138:139], v[110:111], v[166:167]
	v_pk_fma_f32 v[108:109], v[144:145], v[108:109], v[158:159]
	v_pk_fma_f32 v[106:107], v[142:143], v[106:107], v[174:175]
	v_pk_fma_f32 v[104:105], v[136:137], v[104:105], v[160:161]
	v_pk_fma_f32 v[102:103], v[134:135], v[102:103], v[176:177]
	v_pk_fma_f32 v[100:101], v[132:133], v[100:101], v[164:165]
	v_pk_fma_f32 v[98:99], v[130:131], v[98:99], v[178:179]
	v_add_u32_e32 v156, 48, v150
	v_add_u32_e32 v247, 0x40000, v246
	global_load_dwordx2 v[224:225], v247, s[94:95]
	global_load_dwordx2 v[232:233], v247, s[94:95] offset:32
	global_load_dwordx2 v[234:235], v247, s[94:95] offset:256
	global_load_dwordx2 v[236:237], v247, s[94:95] offset:288
	ds_read_b64 v[172:173], v183 offset:8448
	v_ashrrev_i32_e32 v157, 31, v156
	v_lshlrev_b64 v[174:175], 11, v[156:157]
	v_lshl_add_u64 v[174:175], s[94:95], 0, v[174:175]
	v_lshl_add_u64 v[174:175], v[174:175], 0, v[168:169]
	s_waitcnt lgkmcnt(0)
	v_pk_mul_f32 v[94:95], v[94:95], v[172:173] op_sel:[0,1]
	v_pk_mul_f32 v[96:97], v[96:97], v[172:173] op_sel:[0,1]
	v_pk_mul_f32 v[90:91], v[90:91], v[172:173] op_sel:[0,1]
	v_pk_mul_f32 v[92:93], v[92:93], v[172:173] op_sel:[0,1]
	v_pk_mul_f32 v[86:87], v[86:87], v[172:173] op_sel:[0,1]
	v_pk_mul_f32 v[88:89], v[88:89], v[172:173] op_sel:[0,1]
	v_pk_mul_f32 v[82:83], v[82:83], v[172:173] op_sel:[0,1]
	v_pk_mul_f32 v[84:85], v[84:85], v[172:173] op_sel:[0,1]
	s_waitcnt vmcnt(11)
	v_lshlrev_b32_e32 v172, 16, v238
	v_and_b32_e32 v173, 0xffff0000, v238
	v_lshlrev_b32_e32 v158, 16, v239
	v_and_b32_e32 v159, 0xffff0000, v239
	s_waitcnt vmcnt(10)
	v_lshlrev_b32_e32 v176, 16, v240
	v_and_b32_e32 v177, 0xffff0000, v240
	v_lshlrev_b32_e32 v160, 16, v241
	v_and_b32_e32 v161, 0xffff0000, v241
	s_waitcnt vmcnt(9)
	v_lshlrev_b32_e32 v178, 16, v242
	v_and_b32_e32 v179, 0xffff0000, v242
	v_lshlrev_b32_e32 v164, 16, v243
	v_and_b32_e32 v165, 0xffff0000, v243
	s_waitcnt vmcnt(8)
	v_lshlrev_b32_e32 v180, 16, v244
	v_and_b32_e32 v181, 0xffff0000, v244
	v_lshlrev_b32_e32 v166, 16, v245
	v_and_b32_e32 v167, 0xffff0000, v245
	v_pk_fma_f32 v[96:97], v[140:141], v[96:97], v[158:159]
	v_pk_fma_f32 v[94:95], v[138:139], v[94:95], v[172:173]
	v_pk_fma_f32 v[92:93], v[144:145], v[92:93], v[160:161]
	v_pk_fma_f32 v[90:91], v[142:143], v[90:91], v[176:177]
	v_pk_fma_f32 v[88:89], v[136:137], v[88:89], v[164:165]
	v_pk_fma_f32 v[86:87], v[134:135], v[86:87], v[178:179]
	v_pk_fma_f32 v[84:85], v[132:133], v[84:85], v[166:167]
	v_pk_fma_f32 v[82:83], v[130:131], v[82:83], v[180:181]
	v_add_u32_e32 v158, 0x80, v150
	v_add_u32_e32 v247, 0x48000, v246
	global_load_dwordx2 v[238:239], v247, s[94:95]
	global_load_dwordx2 v[240:241], v247, s[94:95] offset:32
	global_load_dwordx2 v[242:243], v247, s[94:95] offset:256
	global_load_dwordx2 v[244:245], v247, s[94:95] offset:288
	ds_read_b64 v[174:175], v183 offset:8576
	v_ashrrev_i32_e32 v159, 31, v158
	v_lshlrev_b64 v[176:177], 11, v[158:159]
	v_lshl_add_u64 v[176:177], s[94:95], 0, v[176:177]
	v_lshl_add_u64 v[176:177], v[176:177], 0, v[168:169]
	s_waitcnt lgkmcnt(0)
	v_pk_mul_f32 v[78:79], v[78:79], v[174:175] op_sel:[0,1]
	v_pk_mul_f32 v[80:81], v[80:81], v[174:175] op_sel:[0,1]
	v_pk_mul_f32 v[74:75], v[74:75], v[174:175] op_sel:[0,1]
	v_pk_mul_f32 v[76:77], v[76:77], v[174:175] op_sel:[0,1]
	v_pk_mul_f32 v[70:71], v[70:71], v[174:175] op_sel:[0,1]
	v_pk_mul_f32 v[72:73], v[72:73], v[174:175] op_sel:[0,1]
	v_pk_mul_f32 v[66:67], v[66:67], v[174:175] op_sel:[0,1]
	v_pk_mul_f32 v[68:69], v[68:69], v[174:175] op_sel:[0,1]
	s_waitcnt vmcnt(11)
	v_lshlrev_b32_e32 v174, 16, v216
	v_and_b32_e32 v175, 0xffff0000, v216
	v_lshlrev_b32_e32 v160, 16, v217
	v_and_b32_e32 v161, 0xffff0000, v217
	s_waitcnt vmcnt(10)
	v_lshlrev_b32_e32 v178, 16, v218
	v_and_b32_e32 v179, 0xffff0000, v218
	v_lshlrev_b32_e32 v164, 16, v219
	v_and_b32_e32 v165, 0xffff0000, v219
	s_waitcnt vmcnt(9)
	v_lshlrev_b32_e32 v180, 16, v220
	v_and_b32_e32 v181, 0xffff0000, v220
	v_lshlrev_b32_e32 v166, 16, v221
	v_and_b32_e32 v167, 0xffff0000, v221
	s_waitcnt vmcnt(8)
	v_lshlrev_b32_e32 v186, 16, v222
	v_and_b32_e32 v187, 0xffff0000, v222
	v_lshlrev_b32_e32 v172, 16, v223
	v_and_b32_e32 v173, 0xffff0000, v223
	v_pk_fma_f32 v[80:81], v[140:141], v[80:81], v[160:161]
	v_pk_fma_f32 v[78:79], v[138:139], v[78:79], v[174:175]
	v_pk_fma_f32 v[76:77], v[144:145], v[76:77], v[164:165]
	v_pk_fma_f32 v[74:75], v[142:143], v[74:75], v[178:179]
	v_pk_fma_f32 v[72:73], v[136:137], v[72:73], v[166:167]
	v_pk_fma_f32 v[70:71], v[134:135], v[70:71], v[180:181]
	v_pk_fma_f32 v[68:69], v[132:133], v[68:69], v[172:173]
	v_pk_fma_f32 v[66:67], v[130:131], v[66:67], v[186:187]
	v_add_u32_e32 v160, 0x90, v150
	v_add_u32_e32 v247, 0x50000, v246
	global_load_dwordx2 v[216:217], v247, s[94:95]
	global_load_dwordx2 v[218:219], v247, s[94:95] offset:32
	global_load_dwordx2 v[220:221], v247, s[94:95] offset:256
	global_load_dwordx2 v[222:223], v247, s[94:95] offset:288
	ds_read_b64 v[176:177], v183 offset:9216
	v_ashrrev_i32_e32 v161, 31, v160
	v_lshlrev_b64 v[178:179], 11, v[160:161]
	v_lshl_add_u64 v[178:179], s[94:95], 0, v[178:179]
	v_lshl_add_u64 v[178:179], v[178:179], 0, v[168:169]
	s_waitcnt lgkmcnt(0)
	v_pk_mul_f32 v[62:63], v[62:63], v[176:177] op_sel:[0,1]
	v_pk_mul_f32 v[64:65], v[64:65], v[176:177] op_sel:[0,1]
	v_pk_mul_f32 v[58:59], v[58:59], v[176:177] op_sel:[0,1]
	v_pk_mul_f32 v[60:61], v[60:61], v[176:177] op_sel:[0,1]
	v_pk_mul_f32 v[54:55], v[54:55], v[176:177] op_sel:[0,1]
	v_pk_mul_f32 v[56:57], v[56:57], v[176:177] op_sel:[0,1]
	v_pk_mul_f32 v[50:51], v[50:51], v[176:177] op_sel:[0,1]
	v_pk_mul_f32 v[52:53], v[52:53], v[176:177] op_sel:[0,1]
	s_waitcnt vmcnt(11)
	v_lshlrev_b32_e32 v176, 16, v224
	v_and_b32_e32 v177, 0xffff0000, v224
	v_lshlrev_b32_e32 v164, 16, v225
	v_and_b32_e32 v165, 0xffff0000, v225
	s_waitcnt vmcnt(10)
	v_lshlrev_b32_e32 v180, 16, v232
	v_and_b32_e32 v181, 0xffff0000, v232
	v_lshlrev_b32_e32 v166, 16, v233
	v_and_b32_e32 v167, 0xffff0000, v233
	s_waitcnt vmcnt(9)
	v_lshlrev_b32_e32 v186, 16, v234
	v_and_b32_e32 v187, 0xffff0000, v234
	v_lshlrev_b32_e32 v172, 16, v235
	v_and_b32_e32 v173, 0xffff0000, v235
	s_waitcnt vmcnt(8)
	v_lshlrev_b32_e32 v188, 16, v236
	v_and_b32_e32 v189, 0xffff0000, v236
	v_lshlrev_b32_e32 v174, 16, v237
	v_and_b32_e32 v175, 0xffff0000, v237
	v_pk_fma_f32 v[64:65], v[140:141], v[64:65], v[164:165]
	v_pk_fma_f32 v[62:63], v[138:139], v[62:63], v[176:177]
	v_pk_fma_f32 v[60:61], v[144:145], v[60:61], v[166:167]
	v_pk_fma_f32 v[58:59], v[142:143], v[58:59], v[180:181]
	v_pk_fma_f32 v[56:57], v[136:137], v[56:57], v[172:173]
	v_pk_fma_f32 v[54:55], v[134:135], v[54:55], v[186:187]
	v_pk_fma_f32 v[52:53], v[132:133], v[52:53], v[174:175]
	v_pk_fma_f32 v[50:51], v[130:131], v[50:51], v[188:189]
	v_add_u32_e32 v164, 0xa0, v150
	v_add_u32_e32 v247, 0x58000, v246
	global_load_dwordx2 v[224:225], v247, s[94:95]
	global_load_dwordx2 v[232:233], v247, s[94:95] offset:32
	global_load_dwordx2 v[234:235], v247, s[94:95] offset:256
	global_load_dwordx2 v[236:237], v247, s[94:95] offset:288
	ds_read_b64 v[178:179], v183 offset:9344
	v_ashrrev_i32_e32 v165, 31, v164
	v_lshlrev_b64 v[180:181], 11, v[164:165]
	v_lshl_add_u64 v[180:181], s[94:95], 0, v[180:181]
	v_lshl_add_u64 v[180:181], v[180:181], 0, v[168:169]
	s_waitcnt lgkmcnt(0)
	v_pk_mul_f32 v[46:47], v[46:47], v[178:179] op_sel:[0,1]
	v_pk_mul_f32 v[48:49], v[48:49], v[178:179] op_sel:[0,1]
	v_pk_mul_f32 v[42:43], v[42:43], v[178:179] op_sel:[0,1]
	v_pk_mul_f32 v[44:45], v[44:45], v[178:179] op_sel:[0,1]
	v_pk_mul_f32 v[38:39], v[38:39], v[178:179] op_sel:[0,1]
	v_pk_mul_f32 v[40:41], v[40:41], v[178:179] op_sel:[0,1]
	v_pk_mul_f32 v[34:35], v[34:35], v[178:179] op_sel:[0,1]
	v_pk_mul_f32 v[36:37], v[36:37], v[178:179] op_sel:[0,1]
	s_waitcnt vmcnt(11)
	v_lshlrev_b32_e32 v178, 16, v238
	v_and_b32_e32 v179, 0xffff0000, v238
	v_lshlrev_b32_e32 v166, 16, v239
	v_and_b32_e32 v167, 0xffff0000, v239
	s_waitcnt vmcnt(10)
	v_lshlrev_b32_e32 v186, 16, v240
	v_and_b32_e32 v187, 0xffff0000, v240
	v_lshlrev_b32_e32 v172, 16, v241
	v_and_b32_e32 v173, 0xffff0000, v241
	s_waitcnt vmcnt(9)
	v_lshlrev_b32_e32 v188, 16, v242
	v_and_b32_e32 v189, 0xffff0000, v242
	v_lshlrev_b32_e32 v174, 16, v243
	v_and_b32_e32 v175, 0xffff0000, v243
	s_waitcnt vmcnt(8)
	v_lshlrev_b32_e32 v190, 16, v244
	v_and_b32_e32 v191, 0xffff0000, v244
	v_lshlrev_b32_e32 v176, 16, v245
	v_and_b32_e32 v177, 0xffff0000, v245
	v_pk_fma_f32 v[48:49], v[140:141], v[48:49], v[166:167]
	v_pk_fma_f32 v[46:47], v[138:139], v[46:47], v[178:179]
	v_pk_fma_f32 v[44:45], v[144:145], v[44:45], v[172:173]
	v_pk_fma_f32 v[42:43], v[142:143], v[42:43], v[186:187]
	v_pk_fma_f32 v[40:41], v[136:137], v[40:41], v[174:175]
	v_pk_fma_f32 v[38:39], v[134:135], v[38:39], v[188:189]
	v_pk_fma_f32 v[36:37], v[132:133], v[36:37], v[176:177]
	v_pk_fma_f32 v[34:35], v[130:131], v[34:35], v[190:191]
	v_add_u32_e32 v166, 0xb0, v150
	ds_read_b64 v[194:195], v183 offset:9472
	v_ashrrev_i32_e32 v167, 31, v166
	v_lshlrev_b64 v[180:181], 11, v[166:167]
	v_lshl_add_u64 v[180:181], s[94:95], 0, v[180:181]
	v_lshl_add_u64 v[168:169], v[180:181], 0, v[168:169]
	v_mov_b32_e32 v180, v119
	v_mov_b32_e32 v181, v120
	v_mov_b32_e32 v186, v118
	v_mov_b32_e32 v187, v121
	v_mov_b32_e32 v188, v123
	v_mov_b32_e32 v189, v124
	v_mov_b32_e32 v190, v122
	v_mov_b32_e32 v191, v125
	s_waitcnt lgkmcnt(0)
	v_pk_mul_f32 v[30:31], v[30:31], v[194:195] op_sel:[0,1]
	v_pk_mul_f32 v[32:33], v[32:33], v[194:195] op_sel:[0,1]
	v_pk_mul_f32 v[26:27], v[26:27], v[194:195] op_sel:[0,1]
	v_pk_mul_f32 v[28:29], v[28:29], v[194:195] op_sel:[0,1]
	v_pk_mul_f32 v[22:23], v[22:23], v[194:195] op_sel:[0,1]
	v_pk_mul_f32 v[24:25], v[24:25], v[194:195] op_sel:[0,1]
	v_pk_mul_f32 v[18:19], v[18:19], v[194:195] op_sel:[0,1]
	v_pk_mul_f32 v[20:21], v[20:21], v[194:195] op_sel:[0,1]
	s_waitcnt vmcnt(7)
	v_lshlrev_b32_e32 v194, 16, v216
	v_and_b32_e32 v195, 0xffff0000, v216
	v_lshlrev_b32_e32 v172, 16, v217
	v_and_b32_e32 v173, 0xffff0000, v217
	s_waitcnt vmcnt(5)
	v_lshlrev_b32_e32 v204, 16, v220
	v_and_b32_e32 v205, 0xffff0000, v220
	v_lshlrev_b32_e32 v176, 16, v221
	v_and_b32_e32 v177, 0xffff0000, v221
	v_pk_fma_f32 v[32:33], v[140:141], v[32:33], v[172:173]
	v_pk_fma_f32 v[24:25], v[136:137], v[24:25], v[176:177]
	v_pk_add_f32 v[172:173], v[180:181], v[186:187]
	v_pk_add_f32 v[176:177], v[188:189], v[190:191]
	v_add_f32_e32 v186, v172, v173
	v_pk_add_f32 v[172:173], v[176:177], v[176:177] op_sel_hi:[0,1]
	s_waitcnt vmcnt(6)
	v_lshlrev_b32_e32 v200, 16, v218
	v_and_b32_e32 v201, 0xffff0000, v218
	v_lshlrev_b32_e32 v174, 16, v219
	v_and_b32_e32 v175, 0xffff0000, v219
	s_waitcnt vmcnt(4)
	v_lshlrev_b32_e32 v206, 16, v222
	v_and_b32_e32 v207, 0xffff0000, v222
	v_lshlrev_b32_e32 v178, 16, v223
	v_and_b32_e32 v179, 0xffff0000, v223
	v_add_f32_e32 v199, 0, v186
	v_mov_b32_e32 v172, v116
	v_pk_fma_f32 v[30:31], v[138:139], v[30:31], v[194:195]
	v_pk_fma_f32 v[28:29], v[144:145], v[28:29], v[174:175]
	v_pk_fma_f32 v[26:27], v[142:143], v[26:27], v[200:201]
	v_pk_fma_f32 v[22:23], v[134:135], v[22:23], v[204:205]
	v_pk_fma_f32 v[20:21], v[132:133], v[20:21], v[178:179]
	v_pk_fma_f32 v[18:19], v[130:131], v[18:19], v[206:207]
	v_pk_add_f32 v[178:179], v[192:193], v[196:197]
	v_pk_add_f32 v[172:173], v[172:173], v[198:199]
	v_pk_add_f32 v[172:173], v[178:179], v[172:173]
	v_add_f32_e32 v168, v172, v173
	v_mov_b32_e32 v169, v168
	s_nop 1
	v_permlane16_swap_b32_e32 v168, v169
	s_waitcnt lgkmcnt(0)
	v_add_f32_e32 v168, v168, v169
	v_mov_b32_e32 v169, v168
	s_nop 1
	v_permlane32_swap_b32_e32 v168, v169
	s_waitcnt lgkmcnt(0)
	v_add_f32_e32 v168, v168, v169
	v_fmamk_f32 v172, v168, 0xbc800000, v121
	v_fmamk_f32 v186, v168, 0xbc800000, v119
	v_fmamk_f32 v188, v168, 0xbc800000, v125
	v_fmamk_f32 v190, v168, 0xbc800000, v123
	v_fmamk_f32 v169, v168, 0xbc800000, v120
	v_fmamk_f32 v173, v168, 0xbc800000, v118
	v_fmamk_f32 v187, v168, 0xbc800000, v124
	v_fmamk_f32 v189, v168, 0xbc800000, v122
	v_fmamk_f32 v192, v168, 0xbc800000, v129
	v_fmamk_f32 v194, v168, 0xbc800000, v127
	v_mul_f32_e32 v186, v186, v186
	v_mul_f32_e32 v172, v172, v172
	v_mul_f32_e32 v190, v190, v190
	v_mul_f32_e32 v188, v188, v188
	v_fmamk_f32 v191, v168, 0xbc800000, v128
	v_fmamk_f32 v193, v168, 0xbc800000, v126
	v_fmamk_f32 v196, v168, 0xbc800000, v117
	v_fmamk_f32 v198, v168, 0xbc800000, v115
	v_mul_f32_e32 v194, v194, v194
	v_mul_f32_e32 v192, v192, v192
	v_fmac_f32_e32 v186, v173, v173
	v_fmac_f32_e32 v172, v169, v169
	v_fmac_f32_e32 v190, v189, v189
	v_fmac_f32_e32 v188, v187, v187
	v_fmamk_f32 v195, v168, 0xbc800000, v116
	v_fmamk_f32 v197, v168, 0xbc800000, v114
	v_mul_f32_e32 v198, v198, v198
	v_mul_f32_e32 v196, v196, v196
	v_fmac_f32_e32 v194, v193, v193
	v_fmac_f32_e32 v192, v191, v191
	v_add_f32_e32 v169, v186, v172
	v_add_f32_e32 v172, v190, v188
	v_fmac_f32_e32 v198, v197, v197
	v_fmac_f32_e32 v196, v195, v195
	v_add_f32_e32 v173, v194, v192
	v_add_f32_e32 v169, v169, v172
	v_add_f32_e32 v186, v198, v196
	v_add_f32_e32 v169, v173, v169
	v_add_f32_e32 v169, v186, v169
	v_mov_b32_e32 v172, v169
	s_nop 1
	v_permlane16_swap_b32_e32 v169, v172
	ds_read_b64 v[186:187], v183 offset:9600
	s_waitcnt lgkmcnt(1)
	v_add_f32_e32 v169, v169, v172
	ds_bpermute_b32 v172, v202, v169
	s_waitcnt lgkmcnt(1)
	v_pk_mul_f32 v[14:15], v[14:15], v[186:187] op_sel:[0,1]
	v_pk_mul_f32 v[16:17], v[16:17], v[186:187] op_sel:[0,1]
	v_pk_mul_f32 v[10:11], v[10:11], v[186:187] op_sel:[0,1]
	v_pk_mul_f32 v[12:13], v[12:13], v[186:187] op_sel:[0,1]
	v_pk_mul_f32 v[6:7], v[6:7], v[186:187] op_sel:[0,1]
	v_pk_mul_f32 v[8:9], v[8:9], v[186:187] op_sel:[0,1]
	v_pk_mul_f32 v[2:3], v[2:3], v[186:187] op_sel:[0,1]
	v_pk_mul_f32 v[4:5], v[4:5], v[186:187] op_sel:[0,1]
	s_waitcnt vmcnt(3)
	v_lshlrev_b32_e32 v186, 16, v224
	v_and_b32_e32 v187, 0xffff0000, v224
	v_lshlrev_b32_e32 v174, 16, v225
	v_and_b32_e32 v175, 0xffff0000, v225
	s_waitcnt vmcnt(2)
	v_lshlrev_b32_e32 v188, 16, v232
	v_and_b32_e32 v189, 0xffff0000, v232
	v_lshlrev_b32_e32 v180, 16, v233
	v_and_b32_e32 v181, 0xffff0000, v233
	s_waitcnt vmcnt(1)
	v_lshlrev_b32_e32 v190, 16, v234
	v_and_b32_e32 v191, 0xffff0000, v234
	v_lshlrev_b32_e32 v176, 16, v235
	v_and_b32_e32 v177, 0xffff0000, v235
	s_waitcnt vmcnt(0)
	v_lshlrev_b32_e32 v192, 16, v236
	v_and_b32_e32 v193, 0xffff0000, v236
	v_lshlrev_b32_e32 v178, 16, v237
	v_and_b32_e32 v179, 0xffff0000, v237
	v_pk_fma_f32 v[16:17], v[140:141], v[16:17], v[174:175]
	v_pk_fma_f32 v[14:15], v[138:139], v[14:15], v[186:187]
	v_pk_fma_f32 v[12:13], v[144:145], v[12:13], v[180:181]
	v_pk_fma_f32 v[10:11], v[142:143], v[10:11], v[188:189]
	v_pk_fma_f32 v[8:9], v[136:137], v[8:9], v[176:177]
	v_pk_fma_f32 v[6:7], v[134:135], v[6:7], v[190:191]
	v_pk_fma_f32 v[4:5], v[132:133], v[4:5], v[178:179]
	v_pk_fma_f32 v[2:3], v[130:131], v[2:3], v[192:193]
	s_nop 0
	s_and_saveexec_b64 s[0:1], s[6:7]
	s_cbranch_execz .LBB0_1493
	s_lshl_b32 s19, s33, 11
	s_add_i32 s19, s17, s19
	v_mul_f32_e32 v130, 0x3c800000, v168
	s_waitcnt lgkmcnt(0)
	v_add_f32_e32 v131, v169, v172
	v_lshl_add_u32 v132, v170, 5, s19
	ds_write_b64 v132, v[130:131]
